# one static s_setprio 1 for the scan consumer waves (0-3, the serial MFMA chain) during the chunked RWKV scan phase
# speedup vs baseline: 1.0149x; 1.0147x over previous
; __device__ __forceinline__ void scan_chunked_phase(LAS unsigned char* lds, unsigned char* wsb, const float* kkw, const float* kaw,
;                                                    const float* w0, const float* a0, const float* rk, const float* lng, const float* lnb, int G, int bid, int mode) {
;     const bf16_t* LDh = (const bf16_t*)(wsb + WS_S0); const bf16_t* Ah = LDh + SLOT / 2; const bf16_t* Gt = LDh + 2 * (SLOT / 2); const bf16_t* R = LDh + 3 * (SLOT / 2);
;     const bf16_t* K = LDh + 4 * (SLOT / 2); const bf16_t* V = LDh + 5 * (SLOT / 2); bf16_t* Y = (bf16_t*)(wsb + WS_S6);
;     int tid_l_ = threadIdx.x; asm volatile("" : "+v"(tid_l_)); const int tid = tid_l_, wave = __builtin_amdgcn_readfirstlane(tid >> 6), lane = tid & 63;
;     constexpr int NR = SEQ / 64;
;     for (int bh = bid; bh < 256; bh += G) {
;         const int b = bh >> 5, h = bh & 31; const size_t base = (size_t)b * SEQ * DM + h * 64;
;         if (wave >= 4) {
;             const int pw = wave - 4;
;             const float kk1 = kkw[h * 64 + lane], ka1 = kaw[h * 64 + lane], w01 = w0[h * 64 + lane], a01 = a0[h * 64 + lane], rk1 = rk[h * 64 + lane];
;             LAS unsigned char* xs = lds + CK_XS + pw * 4352;
;             CkRaw cur;
;             ck_fetch(cur, R, K, V, LDh, Ah, base + (size_t)(pw * 16) * DM, lane);
;             ck_produce_a(lds + pw * CK_SLOT, xs, cur, lane, kk1, ka1, w01, a01, rk1);
;             ck_fetch(cur, R, K, V, LDh, Ah, base + (size_t)(64 + pw * 16) * DM, lane);
;             ck_produce_b(lds + pw * CK_SLOT, lane);
;             __syncthreads();
;             for (int rd = 0; rd < NR; ++rd) {
;                 if (rd + 1 < NR) {
;                     LAS unsigned char* sl = lds + (((rd + 1) & 1) * 4 + pw) * CK_SLOT;
;                     ck_produce_a(sl, xs, cur, lane, kk1, ka1, w01, a01, rk1);
;                     if (rd + 2 < NR) ck_fetch(cur, R, K, V, LDh, Ah, base + (size_t)((rd + 2) * 64 + pw * 16) * DM, lane);
;                     ck_produce_b(sl, lane);
;                 }
;                 __syncthreads();
;             }
;         } else {
;             f32x4 sacc[4];
; #pragma unroll
;             for (int i = 0; i < 4; ++i) sacc[i] = (f32x4){0.f, 0.f, 0.f, 0.f};
;             const int n = lane & 15, g = lane >> 4, col = h * 64 + 16 * wave + n;
;             const float lg1 = lng[col], lb1 = lnb[col];
.LBB0_104:
	s_andn2_b64 vcc, exec, s[18:19]
	s_cbranch_vccnz .LBB0_335
	s_add_u32 s86, s4, 0xe700000
	s_addc_u32 s87, s5, 0
	s_cmp_lt_i32 s22, 12
	s_mov_b64 s[18:19], -1
	s_cbranch_scc1 .LBB0_290
	s_cmp_lt_i32 s22, 13
	s_cbranch_scc1 .LBB0_274
	v_writelane_b32 v255, s74, 11
	s_cmp_lt_i32 s22, 14
	s_mov_b32 s82, s90
	v_writelane_b32 v255, s91, 12
	s_cbranch_scc1 .LBB0_186
	s_cmp_eq_u32 s22, 14
	s_cbranch_scc0 .LBB0_185
	s_waitcnt vmcnt(0)
	v_mov_b32_e32 v0, v208
	s_cmpk_gt_i32 s23, 0xff
	s_nop 0
	v_readfirstlane_b32 s2, v0
	s_cbranch_scc1 .LBB0_185
	s_cmpk_lt_u32 s2, 0x100
	s_cbranch_scc0 .Lscanprio_skip
	s_setprio 1
.Lscanprio_skip:
	s_add_u32 s88, s4, 0x12700000
	s_addc_u32 s89, s5, 0
	s_add_u32 s90, s4, 0x16700000
	v_bfe_u32 v3, v0, 2, 4
	s_addc_u32 s91, s5, 0
	s_ashr_i32 s2, s2, 6
	v_and_b32_e32 v5, 12, v3
	v_and_b32_e32 v160, 63, v0
	s_cmp_lt_i32 s2, 4
	v_lshlrev_b32_e32 v162, 5, v5
	v_lshlrev_b32_e32 v2, 11, v5
	v_or_b32_e32 v4, 1, v5
	v_or_b32_e32 v5, 2, v5
	v_writelane_b32 v255, s17, 14
	s_cselect_b64 s[6:7], -1, 0
	s_lshl_b32 s18, s2, 4
	v_lshlrev_b32_e32 v164, 5, v5
	v_lshlrev_b32_e32 v6, 11, v5
	v_add_lshl_u32 v173, s2, v160, 3
	s_add_i32 s17, s2, -4
	s_mulk_i32 s2, 0x1100
	v_bfe_u32 v5, v0, 4, 2
	v_and_b32_e32 v7, 3, v0
	v_writelane_b32 v255, s6, 15
	v_or_b32_e32 v3, 3, v3
	s_add_i32 s2, s2, 0
	s_lshl_b32 s10, s17, 4
	v_cmp_ne_u32_e64 s[42:43], 0, v7
	v_cmp_ne_u32_e64 s[44:45], 1, v7
	v_cmp_eq_u32_e64 s[46:47], 2, v7
	v_bfe_u32 v7, v0, 2, 2
	v_lshlrev_b32_e32 v10, 2, v5
	v_writelane_b32 v255, s7, 16
	v_and_b32_e32 v1, 15, v0
	v_lshlrev_b32_e32 v165, 5, v3
	v_lshlrev_b32_e32 v8, 11, v3
	v_lshrrev_b32_e32 v3, 1, v0
	s_add_i32 s7, s2, 0x1c000
	s_lshl_b64 s[26:27], s[10:11], 11
	s_lshl_b32 s2, s17, 14
	v_cmp_eq_u32_e64 s[48:49], v7, v5
	s_add_i32 s10, s10, 64
	v_lshlrev_b32_e32 v178, 3, v5
	v_mul_u32_u24_e32 v181, 0x240, v5
	v_mul_u32_u24_e32 v182, 0xa0, v5
	v_mul_u32_u24_e32 v183, 0x120, v5
	v_or_b32_e32 v5, 1, v10
	s_ashr_i32 s19, s18, 31
	v_or_b32_e32 v161, s18, v1
	v_and_b32_e32 v166, 24, v3
	v_or_b32_e32 v3, 48, v160
	v_or_b32_e32 v130, s26, v160
	v_mov_b32_e32 v131, s27
	s_add_i32 s6, s2, 0
	s_lshl_b64 s[26:27], s[10:11], 11
	v_cmp_gt_u32_e64 s[54:55], v1, v5
	v_mul_u32_u24_e32 v184, 40, v5
	v_mul_u32_u24_e32 v185, 0x48, v5
	v_or_b32_e32 v5, 2, v10
	s_lshl_b64 s[18:19], s[18:19], 12
	v_and_b32_e32 v171, 48, v0
	v_mul_u32_u24_e32 v172, 0x48, v3
	v_mov_b32_e32 v3, s6
	s_movk_i32 s2, 0x88
	v_mov_b32_e32 v7, s7
	v_cmp_lt_u32_e64 s[56:57], v1, v5
	v_cmp_gt_u32_e64 s[58:59], v1, v5
	v_or_b32_e32 v5, 3, v10
	s_add_u32 s18, s4, s18
	v_lshlrev_b32_e32 v163, 5, v4
	v_lshlrev_b32_e32 v4, 11, v4
	v_mul_u32_u24_e32 v167, 0x88, v1
	v_mul_u32_u24_e32 v169, 40, v1
	v_mul_u32_u24_e32 v170, 0x48, v1
	v_cmp_eq_u32_e64 s[40:41], 0, v1
	v_lshlrev_b32_e32 v132, 1, v160
	v_mad_u32_u24 v3, v1, s2, v3
	v_lshlrev_b32_e32 v174, 2, v1
	v_writelane_b32 v255, s7, 17
	v_mad_u32_u24 v7, v1, s2, v7
	v_add_u32_e32 v9, s6, v171
	v_lshlrev_b32_e32 v179, 1, v1
	v_cmp_lt_u32_e64 s[50:51], v1, v10
	v_cmp_gt_u32_e64 s[52:53], v1, v10
	v_cmp_lt_u32_e64 s[60:61], v1, v5
	v_cmp_gt_u32_e64 s[62:63], v1, v5
	v_mad_u32_u24 v1, v1, 40, s6
	v_lshlrev_b32_e32 v0, 9, v0
	v_mov_b32_e32 v133, v129
	s_addc_u32 s19, s5, s19
	s_lshl_b32 s2, s78, 6
	v_mul_lo_u32 v168, v161, 40
	v_mul_u32_u24_e32 v175, 0x48, v160
	v_mul_u32_u24_e32 v176, 40, v160
	v_lshlrev_b32_e32 v177, 2, v160
	v_or_b32_e32 v134, s26, v160
	v_mov_b32_e32 v135, s27
	v_add_u32_e32 v180, s6, v179
	v_and_b32_e32 v186, 0x6000, v0
	v_lshl_add_u64 v[136:137], s[18:19], 0, v[132:133]
	s_lshl_b32 s92, s23, 6
	v_writelane_b32 v255, s2, 18
	v_lshlrev_b32_e32 v138, 1, v2
	v_lshlrev_b32_e32 v140, 1, v4
	v_lshlrev_b32_e32 v142, 1, v6
	v_lshlrev_b32_e32 v144, 1, v8
	v_add_u32_e32 v133, v3, v171
	v_add_u32_e32 v187, v9, v167
	v_add_u32_e32 v188, v1, v178
	v_add_u32_e32 v189, v7, v171
	s_mov_b32 s37, s23
	s_mov_b64 s[74:75], s[64:65]
	s_branch .LBB0_113

; __device__ __forceinline__ void scan_chunked_phase(LAS unsigned char* lds, unsigned char* wsb, const float* kkw, const float* kaw,
;                                                    const float* w0, const float* a0, const float* rk, const float* lng, const float* lnb, int G, int bid, int mode) {
;     ...
;         __syncthreads();
;     }
; }
.LBB0_184:
	s_setprio 0
	v_readlane_b32 s88, v254, 63
	v_readlane_b32 s89, v255, 0
	s_movk_i32 s68, 0x4000
	s_mov_b32 s69, 0x10000
	s_mov_b32 s37, 0x14000
	s_mov_b32 s40, 0x18000
	s_mov_b32 s41, 0x8000
	s_mov_b64 s[26:27], 0x1000
	s_mov_b32 s90, s82
	v_readlane_b32 s17, v255, 14
	v_readlane_b32 s91, v255, 12
